# v78 + fused resid-norm epilogue (G3, G5): the ai=1 half's 8 residual loads issued together with the ai=0 half's (renamed into unused registers) instead of behind the ai=0 H stores; counted waits re-de
# speedup vs baseline: 1.0017x; 1.0017x over previous
; __device__ __forceinline__ float bf_lo(unsigned w) { return __uint_as_float(w << 16); }
; __device__ __forceinline__ float bf_hi(unsigned w) { return __uint_as_float(w & 0xffff0000u); }
; __device__ __forceinline__ float sigmoidf_fast(float x) { return __builtin_amdgcn_rcpf(1.0f + __expf(-x)); }
;     __device__ __forceinline__ void fused(f32x4 (&acc)[2][2][4][2], const Unit& u, int wr, int wc, int fr, int fq, PG8_LAS unsigned char* lds, int wid, int lane) const {
;     ...
;         for (int ai = 0; ai < 2; ++ai) {
;             h16x8 hraw[4][2]; u32x4 eraw[4][2];
; #pragma unroll
;             for (int m = 0; m < 4; ++m) { const size_t off = (size_t)(u.pm * BM + ai * HALF + wr * 64 + m * 16 + fr) * ld + col0;
; #pragma unroll
;                 for (int bj = 0; bj < 2; ++bj) { hraw[m][bj] = *(const h16x8*)(H + off + bj * HALF); if (MODE != 0) eraw[m][bj] = *(const u32x4*)(E + off + bj * HALF); } }
; #pragma unroll
;             for (int m = 0; m < 4; ++m) { const size_t off = (size_t)(u.pm * BM + ai * HALF + wr * 64 + m * 16 + fr) * ld + col0;
; #pragma unroll
;                 for (int bj = 0; bj < 2; ++bj) { const f32x8 hv = __builtin_convertvector(hraw[m][bj], f32x8); f32x8 r8;
; #pragma unroll
;                     for (int n = 0; n < 2; ++n) { f32x4 r; const f32x4 a = acc[ai][bj][m][n];
;                         if (MODE == 0) { r[0] = hv[4 * n] + a[0]; r[1] = hv[4 * n + 1] + a[1]; r[2] = hv[4 * n + 2] + a[2]; r[3] = hv[4 * n + 3] + a[3]; }
;                         else { const unsigned e0 = n ? eraw[m][bj].z : eraw[m][bj].x, e1 = n ? eraw[m][bj].w : eraw[m][bj].y;
;                             r[0] = hv[4 * n] + sigmoidf_fast(a[0]) * bf_lo(e0); r[1] = hv[4 * n + 1] + sigmoidf_fast(a[1]) * bf_hi(e0); r[2] = hv[4 * n + 2] + sigmoidf_fast(a[2]) * bf_lo(e1); r[3] = hv[4 * n + 3] + sigmoidf_fast(a[3]) * bf_hi(e1); }
;                         acc[ai][bj][m][n] = r; r8[4 * n] = r[0]; r8[4 * n + 1] = r[1]; r8[4 * n + 2] = r[2]; r8[4 * n + 3] = r[3]; }
;                     *(h16x8*)(H + off + bj * HALF) = __builtin_convertvector(r8, h16x8); }
.LBB0_955:
	s_lshl_b32 s4, s36, 5
	s_lshl_b32 s5, s0, 8
	v_lshrrev_b32_e32 v122, 1, v173
	s_or_b32 s4, s5, s4
	s_lshl_b32 s18, s33, 8
	v_and_or_b32 v160, v122, 24, s4
	s_add_i32 s4, s18, s45
	v_or_b32_e32 v162, s4, v174
	v_ashrrev_i32_e32 v161, 31, v160
	v_readlane_b32 s4, v252, 57
	v_lshlrev_b64 v[158:159], 1, v[160:161]
	v_readlane_b32 s5, v252, 58
	v_ashrrev_i32_e32 v163, 31, v162
	v_lshlrev_b64 v[180:181], 12, v[162:163]
	v_lshl_add_u64 v[164:165], s[4:5], 0, v[158:159]
	v_lshl_add_u64 v[126:127], v[164:165], 0, v[180:181]
	s_barrier
	global_load_dwordx4 v[122:125], v[126:127], off
	s_nop 0
	global_load_dwordx4 v[126:129], v[126:127], off offset:256
	v_or_b32_e32 v138, 16, v162
	v_ashrrev_i32_e32 v139, 31, v138
	v_lshlrev_b64 v[170:171], 12, v[138:139]
	v_lshl_add_u64 v[138:139], v[164:165], 0, v[170:171]
	global_load_dwordx4 v[176:179], v[138:139], off
	global_load_dwordx4 v[154:157], v[138:139], off offset:256
	v_or_b32_e32 v138, 32, v162
	v_ashrrev_i32_e32 v139, 31, v138
	v_lshlrev_b64 v[168:169], 12, v[138:139]
	v_lshl_add_u64 v[138:139], v[164:165], 0, v[168:169]
	global_load_dwordx4 v[150:153], v[138:139], off
	global_load_dwordx4 v[146:149], v[138:139], off offset:256
	v_or_b32_e32 v138, 48, v162
	v_ashrrev_i32_e32 v139, 31, v138
	v_lshlrev_b64 v[166:167], 12, v[138:139]
	v_lshl_add_u64 v[138:139], v[164:165], 0, v[166:167]
	global_load_dwordx4 v[142:145], v[138:139], off
	s_nop 0
	global_load_dwordx4 v[138:141], v[138:139], off offset:256
	v_lshl_add_u64 v[180:181], s[4:5], 0, v[180:181]
	v_lshl_add_u64 v[180:181], v[180:181], 0, v[158:159]
	v_and_b32_e32 v32, 63, v173
	v_add_u32_e32 v188, 0x80, v162
	v_ashrrev_i32_e32 v189, 31, v188
	v_lshlrev_b64 v[190:191], 12, v[188:189]
	v_lshl_add_u64 v[192:193], v[164:165], 0, v[190:191]
	global_load_dwordx4 v[198:201], v[192:193], off
	global_load_dwordx4 v[202:205], v[192:193], off offset:256
	v_add_u32_e32 v188, 0x90, v162
	v_ashrrev_i32_e32 v189, 31, v188
	v_lshlrev_b64 v[190:191], 12, v[188:189]
	v_lshl_add_u64 v[192:193], v[164:165], 0, v[190:191]
	global_load_dwordx4 v[206:209], v[192:193], off
	global_load_dwordx4 v[210:213], v[192:193], off offset:256
	v_add_u32_e32 v188, 0xa0, v162
	v_ashrrev_i32_e32 v189, 31, v188
	v_lshlrev_b64 v[190:191], 12, v[188:189]
	v_lshl_add_u64 v[192:193], v[164:165], 0, v[190:191]
	global_load_dwordx4 v[214:217], v[192:193], off
	global_load_dwordx4 v[218:221], v[192:193], off offset:256
	v_add_u32_e32 v188, 0xb0, v162
	v_ashrrev_i32_e32 v189, 31, v188
	v_lshlrev_b64 v[190:191], 12, v[188:189]
	v_lshl_add_u64 v[192:193], v[164:165], 0, v[190:191]
	global_load_dwordx4 v[222:225], v[192:193], off
	global_load_dwordx4 v[246:249], v[192:193], off offset:256
	s_waitcnt vmcnt(8)
	v_cvt_f32_f16_e32 v182, v125
	v_cvt_f32_f16_sdwa v183, v125 dst_sel:DWORD dst_unused:UNUSED_PAD src0_sel:WORD_1
	v_cvt_f32_f16_e32 v184, v124
	v_cvt_f32_f16_sdwa v185, v124 dst_sel:DWORD dst_unused:UNUSED_PAD src0_sel:WORD_1
	v_cvt_f32_f16_e32 v124, v123
	v_cvt_f32_f16_sdwa v125, v123 dst_sel:DWORD dst_unused:UNUSED_PAD src0_sel:WORD_1
	v_cvt_f32_f16_e32 v186, v122
	v_cvt_f32_f16_sdwa v187, v122 dst_sel:DWORD dst_unused:UNUSED_PAD src0_sel:WORD_1
	v_pk_add_f32 v[114:115], v[114:115], v[184:185]
	v_pk_add_f32 v[120:121], v[120:121], v[124:125]
	v_pk_add_f32 v[116:117], v[116:117], v[182:183]
	v_pk_add_f32 v[118:119], v[118:119], v[186:187]
	v_cvt_pk_f16_f32 v125, v116, v117
	v_cvt_pk_f16_f32 v124, v114, v115
	v_cvt_pk_f16_f32 v123, v120, v121
	v_cvt_pk_f16_f32 v122, v118, v119
	global_store_dwordx4 v[180:181], v[122:125], off
	v_cvt_f32_f16_e32 v182, v126
	v_cvt_f32_f16_sdwa v183, v126 dst_sel:DWORD dst_unused:UNUSED_PAD src0_sel:WORD_1
	v_cvt_f32_f16_e32 v124, v129
	v_cvt_f32_f16_sdwa v125, v129 dst_sel:DWORD dst_unused:UNUSED_PAD src0_sel:WORD_1
	v_cvt_f32_f16_e32 v122, v128
	v_cvt_f32_f16_sdwa v123, v128 dst_sel:DWORD dst_unused:UNUSED_PAD src0_sel:WORD_1
	v_cvt_f32_f16_e32 v128, v127
	v_cvt_f32_f16_sdwa v129, v127 dst_sel:DWORD dst_unused:UNUSED_PAD src0_sel:WORD_1
	v_pk_add_f32 v[126:127], v[106:107], v[182:183]
	v_pk_add_f32 v[122:123], v[102:103], v[122:123]
	v_pk_add_f32 v[124:125], v[104:105], v[124:125]
	v_pk_add_f32 v[128:129], v[108:109], v[128:129]
	v_cvt_pk_f16_f32 v105, v124, v125
	v_cvt_pk_f16_f32 v104, v122, v123
	v_cvt_pk_f16_f32 v103, v128, v129
	v_cvt_pk_f16_f32 v102, v126, v127
	global_store_dwordx4 v[180:181], v[102:105], off offset:256
	v_cvt_f32_f16_e32 v108, v177
	v_cvt_f32_f16_sdwa v109, v177 dst_sel:DWORD dst_unused:UNUSED_PAD src0_sel:WORD_1
	v_cvt_f32_f16_e32 v104, v179
	v_cvt_f32_f16_sdwa v105, v179 dst_sel:DWORD dst_unused:UNUSED_PAD src0_sel:WORD_1
	v_cvt_f32_f16_e32 v102, v178
	v_cvt_f32_f16_sdwa v103, v178 dst_sel:DWORD dst_unused:UNUSED_PAD src0_sel:WORD_1
	v_cvt_f32_f16_e32 v106, v176
	v_cvt_f32_f16_sdwa v107, v176 dst_sel:DWORD dst_unused:UNUSED_PAD src0_sel:WORD_1
	v_pk_add_f32 v[108:109], v[136:137], v[108:109]
	v_pk_add_f32 v[102:103], v[130:131], v[102:103]
	v_pk_add_f32 v[104:105], v[132:133], v[104:105]
	v_pk_add_f32 v[106:107], v[134:135], v[106:107]
	v_lshl_add_u64 v[130:131], s[4:5], 0, v[170:171]
	v_cvt_pk_f16_f32 v135, v104, v105
	v_cvt_pk_f16_f32 v134, v102, v103
	v_cvt_pk_f16_f32 v133, v108, v109
	v_cvt_pk_f16_f32 v132, v106, v107
	v_lshl_add_u64 v[130:131], v[130:131], 0, v[158:159]
	global_store_dwordx4 v[130:131], v[132:135], off
	v_cvt_f32_f16_e32 v136, v155
	v_cvt_f32_f16_sdwa v137, v155 dst_sel:DWORD dst_unused:UNUSED_PAD src0_sel:WORD_1
	v_cvt_f32_f16_e32 v132, v157
	v_cvt_f32_f16_sdwa v133, v157 dst_sel:DWORD dst_unused:UNUSED_PAD src0_sel:WORD_1
	v_cvt_f32_f16_e32 v134, v156
	v_cvt_f32_f16_sdwa v135, v156 dst_sel:DWORD dst_unused:UNUSED_PAD src0_sel:WORD_1
; __device__ __forceinline__ float bf_lo(unsigned w) { return __uint_as_float(w << 16); }
; __device__ __forceinline__ float bf_hi(unsigned w) { return __uint_as_float(w & 0xffff0000u); }
; __device__ __forceinline__ float sigmoidf_fast(float x) { return __builtin_amdgcn_rcpf(1.0f + __expf(-x)); }
;     __device__ __forceinline__ void fused(f32x4 (&acc)[2][2][4][2], const Unit& u, int wr, int wc, int fr, int fq, PG8_LAS unsigned char* lds, int wid, int lane) const {
;     ...
;             for (int m = 0; m < 4; ++m) { const size_t off = (size_t)(u.pm * BM + ai * HALF + wr * 64 + m * 16 + fr) * ld + col0;
; #pragma unroll
;                 for (int bj = 0; bj < 2; ++bj) { const f32x8 hv = __builtin_convertvector(hraw[m][bj], f32x8); f32x8 r8;
; #pragma unroll
;                     for (int n = 0; n < 2; ++n) { f32x4 r; const f32x4 a = acc[ai][bj][m][n];
;                         if (MODE == 0) { r[0] = hv[4 * n] + a[0]; r[1] = hv[4 * n + 1] + a[1]; r[2] = hv[4 * n + 2] + a[2]; r[3] = hv[4 * n + 3] + a[3]; }
;                         else { const unsigned e0 = n ? eraw[m][bj].z : eraw[m][bj].x, e1 = n ? eraw[m][bj].w : eraw[m][bj].y;
;                             r[0] = hv[4 * n] + sigmoidf_fast(a[0]) * bf_lo(e0); r[1] = hv[4 * n + 1] + sigmoidf_fast(a[1]) * bf_hi(e0); r[2] = hv[4 * n + 2] + sigmoidf_fast(a[2]) * bf_lo(e1); r[3] = hv[4 * n + 3] + sigmoidf_fast(a[3]) * bf_hi(e1); }
;                         acc[ai][bj][m][n] = r; r8[4 * n] = r[0]; r8[4 * n + 1] = r[1]; r8[4 * n + 2] = r[2]; r8[4 * n + 3] = r[3]; }
;                     *(h16x8*)(H + off + bj * HALF) = __builtin_convertvector(r8, h16x8); }
	v_cvt_f32_f16_e32 v156, v154
	v_cvt_f32_f16_sdwa v157, v154 dst_sel:DWORD dst_unused:UNUSED_PAD src0_sel:WORD_1
	v_pk_add_f32 v[112:113], v[112:113], v[136:137]
	v_pk_add_f32 v[98:99], v[98:99], v[134:135]
	v_pk_add_f32 v[100:101], v[100:101], v[132:133]
	v_pk_add_f32 v[110:111], v[110:111], v[156:157]
	v_cvt_pk_f16_f32 v135, v100, v101
	v_cvt_pk_f16_f32 v134, v98, v99
	v_cvt_pk_f16_f32 v133, v112, v113
	v_cvt_pk_f16_f32 v132, v110, v111
	global_store_dwordx4 v[130:131], v[132:135], off offset:256
	v_cvt_f32_f16_e32 v130, v153
	v_cvt_f32_f16_sdwa v131, v153 dst_sel:DWORD dst_unused:UNUSED_PAD src0_sel:WORD_1
	v_cvt_f32_f16_e32 v132, v152
	v_cvt_f32_f16_sdwa v133, v152 dst_sel:DWORD dst_unused:UNUSED_PAD src0_sel:WORD_1
	v_cvt_f32_f16_e32 v134, v151
	v_cvt_f32_f16_sdwa v135, v151 dst_sel:DWORD dst_unused:UNUSED_PAD src0_sel:WORD_1
	v_cvt_f32_f16_e32 v136, v150
	v_cvt_f32_f16_sdwa v137, v150 dst_sel:DWORD dst_unused:UNUSED_PAD src0_sel:WORD_1
	v_pk_add_f32 v[90:91], v[90:91], v[132:133]
	v_pk_add_f32 v[96:97], v[96:97], v[134:135]
	v_pk_add_f32 v[92:93], v[92:93], v[130:131]
	v_pk_add_f32 v[94:95], v[94:95], v[136:137]
	v_lshl_add_u64 v[134:135], s[4:5], 0, v[168:169]
	v_cvt_pk_f16_f32 v133, v92, v93
	v_cvt_pk_f16_f32 v132, v90, v91
	v_cvt_pk_f16_f32 v131, v96, v97
	v_cvt_pk_f16_f32 v130, v94, v95
	v_lshl_add_u64 v[134:135], v[134:135], 0, v[158:159]
	global_store_dwordx4 v[134:135], v[130:133], off
	v_cvt_f32_f16_e32 v136, v147
	v_cvt_f32_f16_sdwa v137, v147 dst_sel:DWORD dst_unused:UNUSED_PAD src0_sel:WORD_1
	v_cvt_f32_f16_e32 v130, v149
	v_cvt_f32_f16_sdwa v131, v149 dst_sel:DWORD dst_unused:UNUSED_PAD src0_sel:WORD_1
	v_cvt_f32_f16_e32 v132, v148
	v_cvt_f32_f16_sdwa v133, v148 dst_sel:DWORD dst_unused:UNUSED_PAD src0_sel:WORD_1
	v_cvt_f32_f16_e32 v148, v146
	v_cvt_f32_f16_sdwa v149, v146 dst_sel:DWORD dst_unused:UNUSED_PAD src0_sel:WORD_1
	v_pk_add_f32 v[88:89], v[88:89], v[136:137]
	v_pk_add_f32 v[82:83], v[82:83], v[132:133]
	v_pk_add_f32 v[84:85], v[84:85], v[130:131]
	v_pk_add_f32 v[86:87], v[86:87], v[148:149]
	v_cvt_pk_f16_f32 v133, v84, v85
	v_cvt_pk_f16_f32 v132, v82, v83
	v_cvt_pk_f16_f32 v131, v88, v89
	v_cvt_pk_f16_f32 v130, v86, v87
	global_store_dwordx4 v[134:135], v[130:133], off offset:256
	v_cvt_f32_f16_e32 v134, v143
	v_cvt_f32_f16_sdwa v135, v143 dst_sel:DWORD dst_unused:UNUSED_PAD src0_sel:WORD_1
	v_cvt_f32_f16_e32 v130, v145
	v_cvt_f32_f16_sdwa v131, v145 dst_sel:DWORD dst_unused:UNUSED_PAD src0_sel:WORD_1
	v_cvt_f32_f16_e32 v132, v144
	v_cvt_f32_f16_sdwa v133, v144 dst_sel:DWORD dst_unused:UNUSED_PAD src0_sel:WORD_1
	v_cvt_f32_f16_e32 v136, v142
	v_cvt_f32_f16_sdwa v137, v142 dst_sel:DWORD dst_unused:UNUSED_PAD src0_sel:WORD_1
	v_pk_add_f32 v[80:81], v[80:81], v[134:135]
	v_pk_add_f32 v[74:75], v[74:75], v[132:133]
	v_pk_add_f32 v[76:77], v[76:77], v[130:131]
	v_pk_add_f32 v[78:79], v[78:79], v[136:137]
	v_lshl_add_u64 v[134:135], s[4:5], 0, v[166:167]
	v_cvt_pk_f16_f32 v133, v76, v77
	v_cvt_pk_f16_f32 v132, v74, v75
	v_cvt_pk_f16_f32 v131, v80, v81
	v_cvt_pk_f16_f32 v130, v78, v79
	v_lshl_add_u64 v[134:135], v[134:135], 0, v[158:159]
	global_store_dwordx4 v[134:135], v[130:133], off
	v_cvt_f32_f16_e32 v136, v139
	v_cvt_f32_f16_sdwa v137, v139 dst_sel:DWORD dst_unused:UNUSED_PAD src0_sel:WORD_1
	v_cvt_f32_f16_e32 v130, v141
	v_cvt_f32_f16_sdwa v131, v141 dst_sel:DWORD dst_unused:UNUSED_PAD src0_sel:WORD_1
	v_cvt_f32_f16_e32 v132, v140
	v_cvt_f32_f16_sdwa v133, v140 dst_sel:DWORD dst_unused:UNUSED_PAD src0_sel:WORD_1
	v_cvt_f32_f16_e32 v140, v138
	v_cvt_f32_f16_sdwa v141, v138 dst_sel:DWORD dst_unused:UNUSED_PAD src0_sel:WORD_1
	v_pk_add_f32 v[72:73], v[72:73], v[136:137]
	v_pk_add_f32 v[66:67], v[66:67], v[132:133]
	v_pk_add_f32 v[68:69], v[68:69], v[130:131]
	v_pk_add_f32 v[70:71], v[70:71], v[140:141]
	v_cvt_pk_f16_f32 v133, v68, v69
	v_cvt_pk_f16_f32 v132, v66, v67
	v_cvt_pk_f16_f32 v131, v72, v73
	v_cvt_pk_f16_f32 v130, v70, v71
	global_store_dwordx4 v[134:135], v[130:133], off offset:256
	s_nop 1
	v_add_u32_e32 v130, 0x80, v162
	v_ashrrev_i32_e32 v131, 31, v130
	v_lshlrev_b64 v[170:171], 12, v[130:131]
	v_lshl_add_u64 v[130:131], v[164:165], 0, v[170:171]
	v_add_u32_e32 v130, 0x90, v162
	v_ashrrev_i32_e32 v131, 31, v130
	v_lshlrev_b64 v[180:181], 12, v[130:131]
	v_lshl_add_u64 v[130:131], v[164:165], 0, v[180:181]
	v_add_u32_e32 v130, 0xa0, v162
	v_ashrrev_i32_e32 v131, 31, v130
	v_lshlrev_b64 v[148:149], 12, v[130:131]
	v_lshl_add_u64 v[130:131], v[164:165], 0, v[148:149]
	v_add_u32_e32 v130, 0xb0, v162
	v_ashrrev_i32_e32 v131, 31, v130
	v_lshlrev_b64 v[146:147], 12, v[130:131]
	v_lshl_add_u64 v[130:131], v[164:165], 0, v[146:147]
	s_nop 0
	v_lshl_add_u64 v[148:149], s[4:5], 0, v[148:149]
	v_lshl_add_u64 v[148:149], v[148:149], 0, v[158:159]
	s_waitcnt vmcnt(15)
	v_cvt_f32_f16_e32 v162, v201
	v_cvt_f32_f16_sdwa v163, v201 dst_sel:DWORD dst_unused:UNUSED_PAD src0_sel:WORD_1
	v_cvt_f32_f16_e32 v164, v200
	v_cvt_f32_f16_sdwa v165, v200 dst_sel:DWORD dst_unused:UNUSED_PAD src0_sel:WORD_1
	v_cvt_f32_f16_e32 v152, v199
	v_cvt_f32_f16_sdwa v153, v199 dst_sel:DWORD dst_unused:UNUSED_PAD src0_sel:WORD_1
	v_cvt_f32_f16_e32 v182, v198
	v_cvt_f32_f16_sdwa v183, v198 dst_sel:DWORD dst_unused:UNUSED_PAD src0_sel:WORD_1
	v_pk_add_f32 v[58:59], v[58:59], v[164:165]
	v_pk_add_f32 v[64:65], v[64:65], v[152:153]
	v_pk_add_f32 v[60:61], v[60:61], v[162:163]
	v_pk_add_f32 v[62:63], v[62:63], v[182:183]
	v_lshl_add_u64 v[162:163], s[4:5], 0, v[170:171]
	v_cvt_pk_f16_f32 v153, v60, v61
	v_cvt_pk_f16_f32 v152, v58, v59
	v_cvt_pk_f16_f32 v151, v64, v65
	v_cvt_pk_f16_f32 v150, v62, v63
	v_lshl_add_u64 v[162:163], v[162:163], 0, v[158:159]
	global_store_dwordx4 v[162:163], v[150:153], off
	s_waitcnt vmcnt(15)
; __device__ __forceinline__ float bf_lo(unsigned w) { return __uint_as_float(w << 16); }
; __device__ __forceinline__ float bf_hi(unsigned w) { return __uint_as_float(w & 0xffff0000u); }
; __device__ __forceinline__ float sigmoidf_fast(float x) { return __builtin_amdgcn_rcpf(1.0f + __expf(-x)); }
;     __device__ __forceinline__ void fused(f32x4 (&acc)[2][2][4][2], const Unit& u, int wr, int wc, int fr, int fq, PG8_LAS unsigned char* lds, int wid, int lane) const {
;     ...
;             for (int m = 0; m < 4; ++m) { const size_t off = (size_t)(u.pm * BM + ai * HALF + wr * 64 + m * 16 + fr) * ld + col0;
; #pragma unroll
;                 for (int bj = 0; bj < 2; ++bj) { const f32x8 hv = __builtin_convertvector(hraw[m][bj], f32x8); f32x8 r8;
; #pragma unroll
;                     for (int n = 0; n < 2; ++n) { f32x4 r; const f32x4 a = acc[ai][bj][m][n];
;                         if (MODE == 0) { r[0] = hv[4 * n] + a[0]; r[1] = hv[4 * n + 1] + a[1]; r[2] = hv[4 * n + 2] + a[2]; r[3] = hv[4 * n + 3] + a[3]; }
;                         else { const unsigned e0 = n ? eraw[m][bj].z : eraw[m][bj].x, e1 = n ? eraw[m][bj].w : eraw[m][bj].y;
;                             r[0] = hv[4 * n] + sigmoidf_fast(a[0]) * bf_lo(e0); r[1] = hv[4 * n + 1] + sigmoidf_fast(a[1]) * bf_hi(e0); r[2] = hv[4 * n + 2] + sigmoidf_fast(a[2]) * bf_lo(e1); r[3] = hv[4 * n + 3] + sigmoidf_fast(a[3]) * bf_hi(e1); }
;                         acc[ai][bj][m][n] = r; r8[4 * n] = r[0]; r8[4 * n + 1] = r[1]; r8[4 * n + 2] = r[2]; r8[4 * n + 3] = r[3]; }
;                     *(h16x8*)(H + off + bj * HALF) = __builtin_convertvector(r8, h16x8); }
	v_cvt_f32_f16_e32 v164, v202
	v_cvt_f32_f16_sdwa v165, v202 dst_sel:DWORD dst_unused:UNUSED_PAD src0_sel:WORD_1
	v_cvt_f32_f16_e32 v150, v205
	v_cvt_f32_f16_sdwa v151, v205 dst_sel:DWORD dst_unused:UNUSED_PAD src0_sel:WORD_1
	v_cvt_f32_f16_e32 v152, v204
	v_cvt_f32_f16_sdwa v153, v204 dst_sel:DWORD dst_unused:UNUSED_PAD src0_sel:WORD_1
	v_cvt_f32_f16_e32 v156, v203
	v_cvt_f32_f16_sdwa v157, v203 dst_sel:DWORD dst_unused:UNUSED_PAD src0_sel:WORD_1
	v_pk_add_f32 v[54:55], v[54:55], v[164:165]
	v_pk_add_f32 v[50:51], v[50:51], v[152:153]
	v_pk_add_f32 v[52:53], v[52:53], v[150:151]
	v_pk_add_f32 v[56:57], v[56:57], v[156:157]
	v_cvt_pk_f16_f32 v153, v52, v53
	v_cvt_pk_f16_f32 v152, v50, v51
	v_cvt_pk_f16_f32 v151, v56, v57
	v_cvt_pk_f16_f32 v150, v54, v55
	global_store_dwordx4 v[162:163], v[150:153], off offset:256
	s_waitcnt vmcnt(15)
	v_cvt_f32_f16_e32 v154, v207
	v_cvt_f32_f16_sdwa v155, v207 dst_sel:DWORD dst_unused:UNUSED_PAD src0_sel:WORD_1
	v_cvt_f32_f16_e32 v150, v209
	v_cvt_f32_f16_sdwa v151, v209 dst_sel:DWORD dst_unused:UNUSED_PAD src0_sel:WORD_1
	v_cvt_f32_f16_e32 v152, v208
	v_cvt_f32_f16_sdwa v153, v208 dst_sel:DWORD dst_unused:UNUSED_PAD src0_sel:WORD_1
	v_cvt_f32_f16_e32 v156, v206
	v_cvt_f32_f16_sdwa v157, v206 dst_sel:DWORD dst_unused:UNUSED_PAD src0_sel:WORD_1
	v_pk_add_f32 v[48:49], v[48:49], v[154:155]
	v_pk_add_f32 v[42:43], v[42:43], v[152:153]
	v_pk_add_f32 v[44:45], v[44:45], v[150:151]
	v_pk_add_f32 v[46:47], v[46:47], v[156:157]
	v_lshl_add_u64 v[154:155], s[4:5], 0, v[180:181]
	v_cvt_pk_f16_f32 v153, v44, v45
	v_cvt_pk_f16_f32 v152, v42, v43
	v_cvt_pk_f16_f32 v151, v48, v49
	v_cvt_pk_f16_f32 v150, v46, v47
	v_lshl_add_u64 v[154:155], v[154:155], 0, v[158:159]
	global_store_dwordx4 v[154:155], v[150:153], off
	s_waitcnt vmcnt(15)
	v_cvt_f32_f16_e32 v156, v211
	v_cvt_f32_f16_sdwa v157, v211 dst_sel:DWORD dst_unused:UNUSED_PAD src0_sel:WORD_1
	v_cvt_f32_f16_e32 v150, v213
	v_cvt_f32_f16_sdwa v151, v213 dst_sel:DWORD dst_unused:UNUSED_PAD src0_sel:WORD_1
	v_cvt_f32_f16_e32 v152, v212
	v_cvt_f32_f16_sdwa v153, v212 dst_sel:DWORD dst_unused:UNUSED_PAD src0_sel:WORD_1
	v_cvt_f32_f16_e32 v162, v210
	v_cvt_f32_f16_sdwa v163, v210 dst_sel:DWORD dst_unused:UNUSED_PAD src0_sel:WORD_1
	v_pk_add_f32 v[40:41], v[40:41], v[156:157]
	v_pk_add_f32 v[34:35], v[34:35], v[152:153]
	v_pk_add_f32 v[36:37], v[36:37], v[150:151]
	v_pk_add_f32 v[38:39], v[38:39], v[162:163]
	v_cvt_pk_f16_f32 v153, v36, v37
	v_cvt_pk_f16_f32 v152, v34, v35
	v_cvt_pk_f16_f32 v151, v40, v41
	v_cvt_pk_f16_f32 v150, v38, v39
	global_store_dwordx4 v[154:155], v[150:153], off offset:256
	s_waitcnt vmcnt(15)
	v_cvt_f32_f16_e32 v154, v214
	v_cvt_f32_f16_sdwa v155, v214 dst_sel:DWORD dst_unused:UNUSED_PAD src0_sel:WORD_1
	v_cvt_f32_f16_e32 v150, v217
	v_cvt_f32_f16_sdwa v151, v217 dst_sel:DWORD dst_unused:UNUSED_PAD src0_sel:WORD_1
	v_cvt_f32_f16_e32 v152, v216
	v_cvt_f32_f16_sdwa v153, v216 dst_sel:DWORD dst_unused:UNUSED_PAD src0_sel:WORD_1
	v_cvt_f32_f16_e32 v144, v215
	v_cvt_f32_f16_sdwa v145, v215 dst_sel:DWORD dst_unused:UNUSED_PAD src0_sel:WORD_1
	v_pk_add_f32 v[28:29], v[28:29], v[154:155]
	v_pk_add_f32 v[24:25], v[24:25], v[152:153]
	v_pk_add_f32 v[26:27], v[26:27], v[150:151]
	v_pk_add_f32 v[30:31], v[30:31], v[144:145]
	v_cvt_pk_f16_f32 v145, v26, v27
	v_cvt_pk_f16_f32 v144, v24, v25
	v_cvt_pk_f16_f32 v143, v30, v31
	v_cvt_pk_f16_f32 v142, v28, v29
	global_store_dwordx4 v[148:149], v[142:145], off
	s_waitcnt vmcnt(15)
; __device__ __forceinline__ float bf_lo(unsigned w) { return __uint_as_float(w << 16); }
; __device__ __forceinline__ float bf_hi(unsigned w) { return __uint_as_float(w & 0xffff0000u); }
; __device__ __forceinline__ float sigmoidf_fast(float x) { return __builtin_amdgcn_rcpf(1.0f + __expf(-x)); }
;     __device__ __forceinline__ void run(const f32x4 (&v)[2][2][4][2], const Unit& u, int wr, int wc, int fr, int fq, PG8_LAS unsigned char* lds, int wid, int lane, float inv_n, float eps) const {
;     ...
;         for (int ai = 0; ai < 2; ++ai)
; #pragma unroll
;             for (int m = 0; m < 4; ++m) {
;                 float s = 0.f;
; #pragma unroll
;                 for (int bj = 0; bj < 2; ++bj)
; #pragma unroll
;                     for (int n = 0; n < 2; ++n) { const f32x4 x = v[ai][bj][m][n]; s += (x[0] * x[0] + x[1] * x[1]) + (x[2] * x[2] + x[3] * x[3]); }
;                 s += __shfl_xor(s, 16); s += __shfl_xor(s, 32);
;                 if (fq == 0) P[(ai * HALF + wr * 64 + m * 16 + fr) * 4 + wc] = s;
;     __device__ __forceinline__ void fused(f32x4 (&acc)[2][2][4][2], const Unit& u, int wr, int wc, int fr, int fq, PG8_LAS unsigned char* lds, int wid, int lane) const {
;     ...
;             for (int m = 0; m < 4; ++m) { const size_t off = (size_t)(u.pm * BM + ai * HALF + wr * 64 + m * 16 + fr) * ld + col0;
; #pragma unroll
;                 for (int bj = 0; bj < 2; ++bj) { const f32x8 hv = __builtin_convertvector(hraw[m][bj], f32x8); f32x8 r8;
; #pragma unroll
;                     for (int n = 0; n < 2; ++n) { f32x4 r; const f32x4 a = acc[ai][bj][m][n];
;                         if (MODE == 0) { r[0] = hv[4 * n] + a[0]; r[1] = hv[4 * n + 1] + a[1]; r[2] = hv[4 * n + 2] + a[2]; r[3] = hv[4 * n + 3] + a[3]; }
;                         else { const unsigned e0 = n ? eraw[m][bj].z : eraw[m][bj].x, e1 = n ? eraw[m][bj].w : eraw[m][bj].y;
;                             r[0] = hv[4 * n] + sigmoidf_fast(a[0]) * bf_lo(e0); r[1] = hv[4 * n + 1] + sigmoidf_fast(a[1]) * bf_hi(e0); r[2] = hv[4 * n + 2] + sigmoidf_fast(a[2]) * bf_lo(e1); r[3] = hv[4 * n + 3] + sigmoidf_fast(a[3]) * bf_hi(e1); }
;                         acc[ai][bj][m][n] = r; r8[4 * n] = r[0]; r8[4 * n + 1] = r[1]; r8[4 * n + 2] = r[2]; r8[4 * n + 3] = r[3]; }
;                     *(h16x8*)(H + off + bj * HALF) = __builtin_convertvector(r8, h16x8); }
	v_cvt_f32_f16_e32 v150, v218
	v_cvt_f32_f16_sdwa v151, v218 dst_sel:DWORD dst_unused:UNUSED_PAD src0_sel:WORD_1
	v_cvt_f32_f16_e32 v142, v221
	v_cvt_f32_f16_sdwa v143, v221 dst_sel:DWORD dst_unused:UNUSED_PAD src0_sel:WORD_1
	v_cvt_f32_f16_e32 v144, v220
	v_cvt_f32_f16_sdwa v145, v220 dst_sel:DWORD dst_unused:UNUSED_PAD src0_sel:WORD_1
	v_cvt_f32_f16_e32 v140, v219
	v_cvt_f32_f16_sdwa v141, v219 dst_sel:DWORD dst_unused:UNUSED_PAD src0_sel:WORD_1
	v_pk_add_f32 v[20:21], v[20:21], v[150:151]
	v_pk_add_f32 v[16:17], v[16:17], v[144:145]
	v_pk_add_f32 v[18:19], v[18:19], v[142:143]
	v_pk_add_f32 v[22:23], v[22:23], v[140:141]
	v_cvt_pk_f16_f32 v141, v18, v19
	v_cvt_pk_f16_f32 v140, v16, v17
	v_cvt_pk_f16_f32 v139, v22, v23
	v_cvt_pk_f16_f32 v138, v20, v21
	global_store_dwordx4 v[148:149], v[138:141], off offset:256
	s_waitcnt vmcnt(15)
	v_cvt_f32_f16_e32 v142, v222
	v_cvt_f32_f16_sdwa v143, v222 dst_sel:DWORD dst_unused:UNUSED_PAD src0_sel:WORD_1
	v_cvt_f32_f16_e32 v138, v225
	v_cvt_f32_f16_sdwa v139, v225 dst_sel:DWORD dst_unused:UNUSED_PAD src0_sel:WORD_1
	v_cvt_f32_f16_e32 v140, v224
	v_cvt_f32_f16_sdwa v141, v224 dst_sel:DWORD dst_unused:UNUSED_PAD src0_sel:WORD_1
	v_cvt_f32_f16_e32 v136, v223
	v_cvt_f32_f16_sdwa v137, v223 dst_sel:DWORD dst_unused:UNUSED_PAD src0_sel:WORD_1
	v_pk_add_f32 v[12:13], v[12:13], v[142:143]
	v_pk_add_f32 v[8:9], v[8:9], v[140:141]
	v_pk_add_f32 v[10:11], v[10:11], v[138:139]
	v_pk_add_f32 v[14:15], v[14:15], v[136:137]
	v_lshl_add_u64 v[138:139], s[4:5], 0, v[146:147]
	v_cvt_pk_f16_f32 v137, v10, v11
	v_cvt_pk_f16_f32 v136, v8, v9
	v_cvt_pk_f16_f32 v135, v14, v15
	v_cvt_pk_f16_f32 v134, v12, v13
	v_lshl_add_u64 v[138:139], v[138:139], 0, v[158:159]
	global_store_dwordx4 v[138:139], v[134:137], off
	s_waitcnt vmcnt(15)
	v_cvt_f32_f16_e32 v140, v246
	v_cvt_f32_f16_sdwa v141, v246 dst_sel:DWORD dst_unused:UNUSED_PAD src0_sel:WORD_1
	v_cvt_f32_f16_e32 v134, v249
	v_cvt_f32_f16_sdwa v135, v249 dst_sel:DWORD dst_unused:UNUSED_PAD src0_sel:WORD_1
	v_cvt_f32_f16_e32 v136, v248
	v_cvt_f32_f16_sdwa v137, v248 dst_sel:DWORD dst_unused:UNUSED_PAD src0_sel:WORD_1
	v_cvt_f32_f16_e32 v132, v247
	v_cvt_f32_f16_sdwa v133, v247 dst_sel:DWORD dst_unused:UNUSED_PAD src0_sel:WORD_1
	v_pk_add_f32 v[4:5], v[4:5], v[140:141]
	v_pk_add_f32 v[0:1], v[0:1], v[136:137]
	v_pk_add_f32 v[2:3], v[2:3], v[134:135]
	v_pk_add_f32 v[6:7], v[6:7], v[132:133]
	v_cvt_pk_f16_f32 v133, v2, v3
	v_cvt_pk_f16_f32 v132, v0, v1
	v_cvt_pk_f16_f32 v131, v6, v7
	v_cvt_pk_f16_f32 v130, v4, v5
	global_store_dwordx4 v[138:139], v[130:133], off offset:256
	v_mul_f32_e32 v134, v117, v117
	v_fmac_f32_e32 v134, v116, v116
	v_and_b32_e32 v131, 64, v236
	v_xor_b32_e32 v130, 16, v236
	v_add_u32_e32 v131, 64, v131
	v_cmp_lt_i32_e32 vcc, v130, v131
	v_xor_b32_e32 v132, 32, v236
	v_mul_f32_e32 v133, v121, v121
	v_cndmask_b32_e32 v130, v236, v130, vcc
	v_cmp_lt_i32_e32 vcc, v132, v131
	v_fmac_f32_e32 v133, v120, v120
	v_lshlrev_b32_e32 v130, 2, v130
	v_cndmask_b32_e32 v131, v236, v132, vcc
	v_mul_f32_e32 v132, v119, v119
	v_fmac_f32_e32 v132, v118, v118
	v_add_f32_e32 v132, v132, v133
	v_mul_f32_e32 v133, v115, v115
	v_fmac_f32_e32 v133, v114, v114
	v_add_f32_e32 v133, v133, v134
	v_add_f32_e32 v132, v132, v133
	v_mul_f32_e32 v133, v127, v127
	v_mul_f32_e32 v134, v129, v129
	v_fmac_f32_e32 v133, v126, v126
	v_fmac_f32_e32 v134, v128, v128
	v_add_f32_e32 v133, v133, v134
	v_add_f32_e32 v132, v133, v132
	v_mul_f32_e32 v133, v123, v123
	v_mul_f32_e32 v134, v125, v125
	v_fmac_f32_e32 v133, v122, v122
	v_fmac_f32_e32 v134, v124, v124
	v_add_f32_e32 v133, v133, v134
	v_add_f32_e32 v132, v133, v132
	ds_bpermute_b32 v133, v130, v132
	v_lshlrev_b32_e32 v131, 2, v131
	s_lshl_b32 s4, s36, 2
	s_waitcnt lgkmcnt(0)
	v_add_f32_e32 v132, v132, v133
	ds_bpermute_b32 v133, v131, v132
	v_cmp_gt_u32_e32 vcc, 16, v32
	s_add_i32 s10, s4, 0
	s_and_saveexec_b64 s[4:5], vcc
	s_cbranch_execz .LBB0_957
	s_lshl_b32 s11, s20, 10
	s_add_i32 s11, s10, s11
	v_lshl_add_u32 v134, v174, 4, s11
	s_waitcnt lgkmcnt(0)
	v_add_f32_e32 v132, v132, v133
	ds_write_b32 v134, v132

; __device__ __forceinline__ float bf_lo(unsigned w) { return __uint_as_float(w << 16); }
; __device__ __forceinline__ float bf_hi(unsigned w) { return __uint_as_float(w & 0xffff0000u); }
; __device__ __forceinline__ float sigmoidf_fast(float x) { return __builtin_amdgcn_rcpf(1.0f + __expf(-x)); }
;     __device__ __forceinline__ void fused(f32x4 (&acc)[2][2][4][2], const Unit& u, int wr, int wc, int fr, int fq, PG8_LAS unsigned char* lds, int wid, int lane) const {
;     ...
;         for (int ai = 0; ai < 2; ++ai) {
;             h16x8 hraw[4][2]; u32x4 eraw[4][2];
; #pragma unroll
;             for (int m = 0; m < 4; ++m) { const size_t off = (size_t)(u.pm * BM + ai * HALF + wr * 64 + m * 16 + fr) * ld + col0;
; #pragma unroll
;                 for (int bj = 0; bj < 2; ++bj) { hraw[m][bj] = *(const h16x8*)(H + off + bj * HALF); if (MODE != 0) eraw[m][bj] = *(const u32x4*)(E + off + bj * HALF); } }
; #pragma unroll
;             for (int m = 0; m < 4; ++m) { const size_t off = (size_t)(u.pm * BM + ai * HALF + wr * 64 + m * 16 + fr) * ld + col0;
; #pragma unroll
;                 for (int bj = 0; bj < 2; ++bj) { const f32x8 hv = __builtin_convertvector(hraw[m][bj], f32x8); f32x8 r8;
; #pragma unroll
;                     for (int n = 0; n < 2; ++n) { f32x4 r; const f32x4 a = acc[ai][bj][m][n];
;                         if (MODE == 0) { r[0] = hv[4 * n] + a[0]; r[1] = hv[4 * n + 1] + a[1]; r[2] = hv[4 * n + 2] + a[2]; r[3] = hv[4 * n + 3] + a[3]; }
;                         else { const unsigned e0 = n ? eraw[m][bj].z : eraw[m][bj].x, e1 = n ? eraw[m][bj].w : eraw[m][bj].y;
;                             r[0] = hv[4 * n] + sigmoidf_fast(a[0]) * bf_lo(e0); r[1] = hv[4 * n + 1] + sigmoidf_fast(a[1]) * bf_hi(e0); r[2] = hv[4 * n + 2] + sigmoidf_fast(a[2]) * bf_lo(e1); r[3] = hv[4 * n + 3] + sigmoidf_fast(a[3]) * bf_hi(e1); }
;                         acc[ai][bj][m][n] = r; r8[4 * n] = r[0]; r8[4 * n + 1] = r[1]; r8[4 * n + 2] = r[2]; r8[4 * n + 3] = r[3]; }
;                     *(h16x8*)(H + off + bj * HALF) = __builtin_convertvector(r8, h16x8); }
.LBB0_1177:
	s_lshl_b32 s4, s36, 5
	s_lshl_b32 s5, s0, 8
	v_lshrrev_b32_e32 v122, 1, v173
	s_or_b32 s4, s5, s4
	s_lshl_b32 s22, s33, 8
	v_and_or_b32 v160, v122, 24, s4
	s_add_i32 s4, s22, s45
	v_or_b32_e32 v162, s4, v174
	v_ashrrev_i32_e32 v161, 31, v160
	v_readlane_b32 s4, v252, 57
	v_lshlrev_b64 v[158:159], 1, v[160:161]
	v_readlane_b32 s5, v252, 58
	v_ashrrev_i32_e32 v163, 31, v162
	v_lshlrev_b64 v[180:181], 12, v[162:163]
	v_lshl_add_u64 v[164:165], s[4:5], 0, v[158:159]
	v_lshl_add_u64 v[126:127], v[164:165], 0, v[180:181]
	s_barrier
	global_load_dwordx4 v[122:125], v[126:127], off
	s_nop 0
	global_load_dwordx4 v[126:129], v[126:127], off offset:256
	v_or_b32_e32 v138, 16, v162
	v_ashrrev_i32_e32 v139, 31, v138
	v_lshlrev_b64 v[170:171], 12, v[138:139]
	v_lshl_add_u64 v[138:139], v[164:165], 0, v[170:171]
	global_load_dwordx4 v[176:179], v[138:139], off
	global_load_dwordx4 v[154:157], v[138:139], off offset:256
	v_or_b32_e32 v138, 32, v162
	v_ashrrev_i32_e32 v139, 31, v138
	v_lshlrev_b64 v[168:169], 12, v[138:139]
	v_lshl_add_u64 v[138:139], v[164:165], 0, v[168:169]
	global_load_dwordx4 v[150:153], v[138:139], off
	global_load_dwordx4 v[146:149], v[138:139], off offset:256
	v_or_b32_e32 v138, 48, v162
	v_ashrrev_i32_e32 v139, 31, v138
	v_lshlrev_b64 v[166:167], 12, v[138:139]
	v_lshl_add_u64 v[138:139], v[164:165], 0, v[166:167]
	global_load_dwordx4 v[142:145], v[138:139], off
	s_nop 0
	global_load_dwordx4 v[138:141], v[138:139], off offset:256
	v_lshl_add_u64 v[180:181], s[4:5], 0, v[180:181]
	v_lshl_add_u64 v[180:181], v[180:181], 0, v[158:159]
	v_and_b32_e32 v32, 63, v173
	v_add_u32_e32 v188, 0x80, v162
	v_ashrrev_i32_e32 v189, 31, v188
	v_lshlrev_b64 v[190:191], 12, v[188:189]
	v_lshl_add_u64 v[192:193], v[164:165], 0, v[190:191]
	global_load_dwordx4 v[198:201], v[192:193], off
	global_load_dwordx4 v[202:205], v[192:193], off offset:256
	v_add_u32_e32 v188, 0x90, v162
	v_ashrrev_i32_e32 v189, 31, v188
	v_lshlrev_b64 v[190:191], 12, v[188:189]
	v_lshl_add_u64 v[192:193], v[164:165], 0, v[190:191]
	global_load_dwordx4 v[206:209], v[192:193], off
	global_load_dwordx4 v[210:213], v[192:193], off offset:256
	v_add_u32_e32 v188, 0xa0, v162
	v_ashrrev_i32_e32 v189, 31, v188
	v_lshlrev_b64 v[190:191], 12, v[188:189]
	v_lshl_add_u64 v[192:193], v[164:165], 0, v[190:191]
	global_load_dwordx4 v[214:217], v[192:193], off
	global_load_dwordx4 v[218:221], v[192:193], off offset:256
	v_add_u32_e32 v188, 0xb0, v162
	v_ashrrev_i32_e32 v189, 31, v188
	v_lshlrev_b64 v[190:191], 12, v[188:189]
	v_lshl_add_u64 v[192:193], v[164:165], 0, v[190:191]
	global_load_dwordx4 v[222:225], v[192:193], off
	global_load_dwordx4 v[246:249], v[192:193], off offset:256
	s_waitcnt vmcnt(8)
	v_cvt_f32_f16_e32 v182, v125
	v_cvt_f32_f16_sdwa v183, v125 dst_sel:DWORD dst_unused:UNUSED_PAD src0_sel:WORD_1
	v_cvt_f32_f16_e32 v184, v124
	v_cvt_f32_f16_sdwa v185, v124 dst_sel:DWORD dst_unused:UNUSED_PAD src0_sel:WORD_1
	v_cvt_f32_f16_e32 v124, v123
	v_cvt_f32_f16_sdwa v125, v123 dst_sel:DWORD dst_unused:UNUSED_PAD src0_sel:WORD_1
	v_cvt_f32_f16_e32 v186, v122
	v_cvt_f32_f16_sdwa v187, v122 dst_sel:DWORD dst_unused:UNUSED_PAD src0_sel:WORD_1
	v_pk_add_f32 v[114:115], v[114:115], v[184:185]
	v_pk_add_f32 v[120:121], v[120:121], v[124:125]
	v_pk_add_f32 v[116:117], v[116:117], v[182:183]
	v_pk_add_f32 v[118:119], v[118:119], v[186:187]
	v_cvt_pk_f16_f32 v125, v116, v117
	v_cvt_pk_f16_f32 v124, v114, v115
	v_cvt_pk_f16_f32 v123, v120, v121
	v_cvt_pk_f16_f32 v122, v118, v119
	global_store_dwordx4 v[180:181], v[122:125], off
	v_cvt_f32_f16_e32 v182, v126
	v_cvt_f32_f16_sdwa v183, v126 dst_sel:DWORD dst_unused:UNUSED_PAD src0_sel:WORD_1
	v_cvt_f32_f16_e32 v124, v129
	v_cvt_f32_f16_sdwa v125, v129 dst_sel:DWORD dst_unused:UNUSED_PAD src0_sel:WORD_1
	v_cvt_f32_f16_e32 v122, v128
	v_cvt_f32_f16_sdwa v123, v128 dst_sel:DWORD dst_unused:UNUSED_PAD src0_sel:WORD_1
	v_cvt_f32_f16_e32 v128, v127
	v_cvt_f32_f16_sdwa v129, v127 dst_sel:DWORD dst_unused:UNUSED_PAD src0_sel:WORD_1
	v_pk_add_f32 v[126:127], v[102:103], v[182:183]
	v_pk_add_f32 v[122:123], v[98:99], v[122:123]
	v_pk_add_f32 v[124:125], v[100:101], v[124:125]
	v_pk_add_f32 v[128:129], v[104:105], v[128:129]
	v_cvt_pk_f16_f32 v101, v124, v125
	v_cvt_pk_f16_f32 v100, v122, v123
	v_cvt_pk_f16_f32 v99, v128, v129
	v_cvt_pk_f16_f32 v98, v126, v127
	global_store_dwordx4 v[180:181], v[98:101], off offset:256
	v_cvt_f32_f16_e32 v104, v177
	v_cvt_f32_f16_sdwa v105, v177 dst_sel:DWORD dst_unused:UNUSED_PAD src0_sel:WORD_1
	v_cvt_f32_f16_e32 v100, v179
	v_cvt_f32_f16_sdwa v101, v179 dst_sel:DWORD dst_unused:UNUSED_PAD src0_sel:WORD_1
	v_cvt_f32_f16_e32 v98, v178
	v_cvt_f32_f16_sdwa v99, v178 dst_sel:DWORD dst_unused:UNUSED_PAD src0_sel:WORD_1
	v_cvt_f32_f16_e32 v102, v176
	v_cvt_f32_f16_sdwa v103, v176 dst_sel:DWORD dst_unused:UNUSED_PAD src0_sel:WORD_1
	v_pk_add_f32 v[104:105], v[136:137], v[104:105]
	v_pk_add_f32 v[98:99], v[130:131], v[98:99]
	v_pk_add_f32 v[100:101], v[132:133], v[100:101]
	v_pk_add_f32 v[102:103], v[134:135], v[102:103]
	v_lshl_add_u64 v[130:131], s[4:5], 0, v[170:171]
	v_cvt_pk_f16_f32 v135, v100, v101
	v_cvt_pk_f16_f32 v134, v98, v99
	v_cvt_pk_f16_f32 v133, v104, v105
	v_cvt_pk_f16_f32 v132, v102, v103
	v_lshl_add_u64 v[130:131], v[130:131], 0, v[158:159]
	global_store_dwordx4 v[130:131], v[132:135], off
	v_cvt_f32_f16_e32 v136, v155
	v_cvt_f32_f16_sdwa v137, v155 dst_sel:DWORD dst_unused:UNUSED_PAD src0_sel:WORD_1
	v_cvt_f32_f16_e32 v132, v157
	v_cvt_f32_f16_sdwa v133, v157 dst_sel:DWORD dst_unused:UNUSED_PAD src0_sel:WORD_1
	v_cvt_f32_f16_e32 v134, v156
	v_cvt_f32_f16_sdwa v135, v156 dst_sel:DWORD dst_unused:UNUSED_PAD src0_sel:WORD_1
; __device__ __forceinline__ float bf_lo(unsigned w) { return __uint_as_float(w << 16); }
; __device__ __forceinline__ float bf_hi(unsigned w) { return __uint_as_float(w & 0xffff0000u); }
; __device__ __forceinline__ float sigmoidf_fast(float x) { return __builtin_amdgcn_rcpf(1.0f + __expf(-x)); }
;     __device__ __forceinline__ void fused(f32x4 (&acc)[2][2][4][2], const Unit& u, int wr, int wc, int fr, int fq, PG8_LAS unsigned char* lds, int wid, int lane) const {
;     ...
;             for (int m = 0; m < 4; ++m) { const size_t off = (size_t)(u.pm * BM + ai * HALF + wr * 64 + m * 16 + fr) * ld + col0;
; #pragma unroll
;                 for (int bj = 0; bj < 2; ++bj) { const f32x8 hv = __builtin_convertvector(hraw[m][bj], f32x8); f32x8 r8;
; #pragma unroll
;                     for (int n = 0; n < 2; ++n) { f32x4 r; const f32x4 a = acc[ai][bj][m][n];
;                         if (MODE == 0) { r[0] = hv[4 * n] + a[0]; r[1] = hv[4 * n + 1] + a[1]; r[2] = hv[4 * n + 2] + a[2]; r[3] = hv[4 * n + 3] + a[3]; }
;                         else { const unsigned e0 = n ? eraw[m][bj].z : eraw[m][bj].x, e1 = n ? eraw[m][bj].w : eraw[m][bj].y;
;                             r[0] = hv[4 * n] + sigmoidf_fast(a[0]) * bf_lo(e0); r[1] = hv[4 * n + 1] + sigmoidf_fast(a[1]) * bf_hi(e0); r[2] = hv[4 * n + 2] + sigmoidf_fast(a[2]) * bf_lo(e1); r[3] = hv[4 * n + 3] + sigmoidf_fast(a[3]) * bf_hi(e1); }
;                         acc[ai][bj][m][n] = r; r8[4 * n] = r[0]; r8[4 * n + 1] = r[1]; r8[4 * n + 2] = r[2]; r8[4 * n + 3] = r[3]; }
;                     *(h16x8*)(H + off + bj * HALF) = __builtin_convertvector(r8, h16x8); }
	v_cvt_f32_f16_e32 v156, v154
	v_cvt_f32_f16_sdwa v157, v154 dst_sel:DWORD dst_unused:UNUSED_PAD src0_sel:WORD_1
	v_pk_add_f32 v[112:113], v[112:113], v[136:137]
	v_pk_add_f32 v[106:107], v[106:107], v[134:135]
	v_pk_add_f32 v[108:109], v[108:109], v[132:133]
	v_pk_add_f32 v[110:111], v[110:111], v[156:157]
	v_cvt_pk_f16_f32 v135, v108, v109
	v_cvt_pk_f16_f32 v134, v106, v107
	v_cvt_pk_f16_f32 v133, v112, v113
	v_cvt_pk_f16_f32 v132, v110, v111
	global_store_dwordx4 v[130:131], v[132:135], off offset:256
	v_cvt_f32_f16_e32 v130, v153
	v_cvt_f32_f16_sdwa v131, v153 dst_sel:DWORD dst_unused:UNUSED_PAD src0_sel:WORD_1
	v_cvt_f32_f16_e32 v132, v152
	v_cvt_f32_f16_sdwa v133, v152 dst_sel:DWORD dst_unused:UNUSED_PAD src0_sel:WORD_1
	v_cvt_f32_f16_e32 v134, v151
	v_cvt_f32_f16_sdwa v135, v151 dst_sel:DWORD dst_unused:UNUSED_PAD src0_sel:WORD_1
	v_cvt_f32_f16_e32 v136, v150
	v_cvt_f32_f16_sdwa v137, v150 dst_sel:DWORD dst_unused:UNUSED_PAD src0_sel:WORD_1
	v_pk_add_f32 v[90:91], v[90:91], v[132:133]
	v_pk_add_f32 v[96:97], v[96:97], v[134:135]
	v_pk_add_f32 v[92:93], v[92:93], v[130:131]
	v_pk_add_f32 v[94:95], v[94:95], v[136:137]
	v_lshl_add_u64 v[134:135], s[4:5], 0, v[168:169]
	v_cvt_pk_f16_f32 v133, v92, v93
	v_cvt_pk_f16_f32 v132, v90, v91
	v_cvt_pk_f16_f32 v131, v96, v97
	v_cvt_pk_f16_f32 v130, v94, v95
	v_lshl_add_u64 v[134:135], v[134:135], 0, v[158:159]
	global_store_dwordx4 v[134:135], v[130:133], off
	v_cvt_f32_f16_e32 v136, v147
	v_cvt_f32_f16_sdwa v137, v147 dst_sel:DWORD dst_unused:UNUSED_PAD src0_sel:WORD_1
	v_cvt_f32_f16_e32 v130, v149
	v_cvt_f32_f16_sdwa v131, v149 dst_sel:DWORD dst_unused:UNUSED_PAD src0_sel:WORD_1
	v_cvt_f32_f16_e32 v132, v148
	v_cvt_f32_f16_sdwa v133, v148 dst_sel:DWORD dst_unused:UNUSED_PAD src0_sel:WORD_1
	v_cvt_f32_f16_e32 v148, v146
	v_cvt_f32_f16_sdwa v149, v146 dst_sel:DWORD dst_unused:UNUSED_PAD src0_sel:WORD_1
	v_pk_add_f32 v[88:89], v[88:89], v[136:137]
	v_pk_add_f32 v[82:83], v[82:83], v[132:133]
	v_pk_add_f32 v[84:85], v[84:85], v[130:131]
	v_pk_add_f32 v[86:87], v[86:87], v[148:149]
	v_cvt_pk_f16_f32 v133, v84, v85
	v_cvt_pk_f16_f32 v132, v82, v83
	v_cvt_pk_f16_f32 v131, v88, v89
	v_cvt_pk_f16_f32 v130, v86, v87
	global_store_dwordx4 v[134:135], v[130:133], off offset:256
	v_cvt_f32_f16_e32 v134, v143
	v_cvt_f32_f16_sdwa v135, v143 dst_sel:DWORD dst_unused:UNUSED_PAD src0_sel:WORD_1
	v_cvt_f32_f16_e32 v130, v145
	v_cvt_f32_f16_sdwa v131, v145 dst_sel:DWORD dst_unused:UNUSED_PAD src0_sel:WORD_1
	v_cvt_f32_f16_e32 v132, v144
	v_cvt_f32_f16_sdwa v133, v144 dst_sel:DWORD dst_unused:UNUSED_PAD src0_sel:WORD_1
	v_cvt_f32_f16_e32 v136, v142
	v_cvt_f32_f16_sdwa v137, v142 dst_sel:DWORD dst_unused:UNUSED_PAD src0_sel:WORD_1
	v_pk_add_f32 v[80:81], v[80:81], v[134:135]
	v_pk_add_f32 v[74:75], v[74:75], v[132:133]
	v_pk_add_f32 v[76:77], v[76:77], v[130:131]
	v_pk_add_f32 v[78:79], v[78:79], v[136:137]
	v_lshl_add_u64 v[134:135], s[4:5], 0, v[166:167]
	v_cvt_pk_f16_f32 v133, v76, v77
	v_cvt_pk_f16_f32 v132, v74, v75
	v_cvt_pk_f16_f32 v131, v80, v81
	v_cvt_pk_f16_f32 v130, v78, v79
	v_lshl_add_u64 v[134:135], v[134:135], 0, v[158:159]
	global_store_dwordx4 v[134:135], v[130:133], off
	v_cvt_f32_f16_e32 v136, v139
	v_cvt_f32_f16_sdwa v137, v139 dst_sel:DWORD dst_unused:UNUSED_PAD src0_sel:WORD_1
	v_cvt_f32_f16_e32 v130, v141
	v_cvt_f32_f16_sdwa v131, v141 dst_sel:DWORD dst_unused:UNUSED_PAD src0_sel:WORD_1
	v_cvt_f32_f16_e32 v132, v140
	v_cvt_f32_f16_sdwa v133, v140 dst_sel:DWORD dst_unused:UNUSED_PAD src0_sel:WORD_1
	v_cvt_f32_f16_e32 v140, v138
	v_cvt_f32_f16_sdwa v141, v138 dst_sel:DWORD dst_unused:UNUSED_PAD src0_sel:WORD_1
	v_pk_add_f32 v[72:73], v[72:73], v[136:137]
	v_pk_add_f32 v[66:67], v[66:67], v[132:133]
	v_pk_add_f32 v[68:69], v[68:69], v[130:131]
	v_pk_add_f32 v[70:71], v[70:71], v[140:141]
	v_cvt_pk_f16_f32 v133, v68, v69
	v_cvt_pk_f16_f32 v132, v66, v67
	v_cvt_pk_f16_f32 v131, v72, v73
	v_cvt_pk_f16_f32 v130, v70, v71
	global_store_dwordx4 v[134:135], v[130:133], off offset:256
	s_nop 1
	v_add_u32_e32 v130, 0x80, v162
	v_ashrrev_i32_e32 v131, 31, v130
	v_lshlrev_b64 v[170:171], 12, v[130:131]
	v_lshl_add_u64 v[130:131], v[164:165], 0, v[170:171]
	v_add_u32_e32 v130, 0x90, v162
	v_ashrrev_i32_e32 v131, 31, v130
	v_lshlrev_b64 v[180:181], 12, v[130:131]
	v_lshl_add_u64 v[130:131], v[164:165], 0, v[180:181]
	v_add_u32_e32 v130, 0xa0, v162
	v_ashrrev_i32_e32 v131, 31, v130
	v_lshlrev_b64 v[148:149], 12, v[130:131]
	v_lshl_add_u64 v[130:131], v[164:165], 0, v[148:149]
	v_add_u32_e32 v130, 0xb0, v162
	v_ashrrev_i32_e32 v131, 31, v130
	v_lshlrev_b64 v[146:147], 12, v[130:131]
	v_lshl_add_u64 v[130:131], v[164:165], 0, v[146:147]
	s_nop 0
	v_lshl_add_u64 v[148:149], s[4:5], 0, v[148:149]
	v_lshl_add_u64 v[148:149], v[148:149], 0, v[158:159]
	s_waitcnt vmcnt(15)
	v_cvt_f32_f16_e32 v162, v201
	v_cvt_f32_f16_sdwa v163, v201 dst_sel:DWORD dst_unused:UNUSED_PAD src0_sel:WORD_1
	v_cvt_f32_f16_e32 v164, v200
	v_cvt_f32_f16_sdwa v165, v200 dst_sel:DWORD dst_unused:UNUSED_PAD src0_sel:WORD_1
	v_cvt_f32_f16_e32 v152, v199
	v_cvt_f32_f16_sdwa v153, v199 dst_sel:DWORD dst_unused:UNUSED_PAD src0_sel:WORD_1
	v_cvt_f32_f16_e32 v182, v198
	v_cvt_f32_f16_sdwa v183, v198 dst_sel:DWORD dst_unused:UNUSED_PAD src0_sel:WORD_1
	v_pk_add_f32 v[58:59], v[58:59], v[164:165]
	v_pk_add_f32 v[64:65], v[64:65], v[152:153]
	v_pk_add_f32 v[60:61], v[60:61], v[162:163]
	v_pk_add_f32 v[62:63], v[62:63], v[182:183]
	v_lshl_add_u64 v[162:163], s[4:5], 0, v[170:171]
	v_cvt_pk_f16_f32 v153, v60, v61
	v_cvt_pk_f16_f32 v152, v58, v59
	v_cvt_pk_f16_f32 v151, v64, v65
	v_cvt_pk_f16_f32 v150, v62, v63
	v_lshl_add_u64 v[162:163], v[162:163], 0, v[158:159]
	global_store_dwordx4 v[162:163], v[150:153], off
	s_waitcnt vmcnt(15)
; __device__ __forceinline__ float bf_lo(unsigned w) { return __uint_as_float(w << 16); }
; __device__ __forceinline__ float bf_hi(unsigned w) { return __uint_as_float(w & 0xffff0000u); }
; __device__ __forceinline__ float sigmoidf_fast(float x) { return __builtin_amdgcn_rcpf(1.0f + __expf(-x)); }
;     __device__ __forceinline__ void fused(f32x4 (&acc)[2][2][4][2], const Unit& u, int wr, int wc, int fr, int fq, PG8_LAS unsigned char* lds, int wid, int lane) const {
;     ...
;             for (int m = 0; m < 4; ++m) { const size_t off = (size_t)(u.pm * BM + ai * HALF + wr * 64 + m * 16 + fr) * ld + col0;
; #pragma unroll
;                 for (int bj = 0; bj < 2; ++bj) { const f32x8 hv = __builtin_convertvector(hraw[m][bj], f32x8); f32x8 r8;
; #pragma unroll
;                     for (int n = 0; n < 2; ++n) { f32x4 r; const f32x4 a = acc[ai][bj][m][n];
;                         if (MODE == 0) { r[0] = hv[4 * n] + a[0]; r[1] = hv[4 * n + 1] + a[1]; r[2] = hv[4 * n + 2] + a[2]; r[3] = hv[4 * n + 3] + a[3]; }
;                         else { const unsigned e0 = n ? eraw[m][bj].z : eraw[m][bj].x, e1 = n ? eraw[m][bj].w : eraw[m][bj].y;
;                             r[0] = hv[4 * n] + sigmoidf_fast(a[0]) * bf_lo(e0); r[1] = hv[4 * n + 1] + sigmoidf_fast(a[1]) * bf_hi(e0); r[2] = hv[4 * n + 2] + sigmoidf_fast(a[2]) * bf_lo(e1); r[3] = hv[4 * n + 3] + sigmoidf_fast(a[3]) * bf_hi(e1); }
;                         acc[ai][bj][m][n] = r; r8[4 * n] = r[0]; r8[4 * n + 1] = r[1]; r8[4 * n + 2] = r[2]; r8[4 * n + 3] = r[3]; }
;                     *(h16x8*)(H + off + bj * HALF) = __builtin_convertvector(r8, h16x8); }
	v_cvt_f32_f16_e32 v164, v202
	v_cvt_f32_f16_sdwa v165, v202 dst_sel:DWORD dst_unused:UNUSED_PAD src0_sel:WORD_1
	v_cvt_f32_f16_e32 v150, v205
	v_cvt_f32_f16_sdwa v151, v205 dst_sel:DWORD dst_unused:UNUSED_PAD src0_sel:WORD_1
	v_cvt_f32_f16_e32 v152, v204
	v_cvt_f32_f16_sdwa v153, v204 dst_sel:DWORD dst_unused:UNUSED_PAD src0_sel:WORD_1
	v_cvt_f32_f16_e32 v156, v203
	v_cvt_f32_f16_sdwa v157, v203 dst_sel:DWORD dst_unused:UNUSED_PAD src0_sel:WORD_1
	v_pk_add_f32 v[54:55], v[54:55], v[164:165]
	v_pk_add_f32 v[50:51], v[50:51], v[152:153]
	v_pk_add_f32 v[52:53], v[52:53], v[150:151]
	v_pk_add_f32 v[56:57], v[56:57], v[156:157]
	v_cvt_pk_f16_f32 v153, v52, v53
	v_cvt_pk_f16_f32 v152, v50, v51
	v_cvt_pk_f16_f32 v151, v56, v57
	v_cvt_pk_f16_f32 v150, v54, v55
	global_store_dwordx4 v[162:163], v[150:153], off offset:256
	s_waitcnt vmcnt(15)
	v_cvt_f32_f16_e32 v154, v207
	v_cvt_f32_f16_sdwa v155, v207 dst_sel:DWORD dst_unused:UNUSED_PAD src0_sel:WORD_1
	v_cvt_f32_f16_e32 v150, v209
	v_cvt_f32_f16_sdwa v151, v209 dst_sel:DWORD dst_unused:UNUSED_PAD src0_sel:WORD_1
	v_cvt_f32_f16_e32 v152, v208
	v_cvt_f32_f16_sdwa v153, v208 dst_sel:DWORD dst_unused:UNUSED_PAD src0_sel:WORD_1
	v_cvt_f32_f16_e32 v156, v206
	v_cvt_f32_f16_sdwa v157, v206 dst_sel:DWORD dst_unused:UNUSED_PAD src0_sel:WORD_1
	v_pk_add_f32 v[48:49], v[48:49], v[154:155]
	v_pk_add_f32 v[42:43], v[42:43], v[152:153]
	v_pk_add_f32 v[44:45], v[44:45], v[150:151]
	v_pk_add_f32 v[46:47], v[46:47], v[156:157]
	v_lshl_add_u64 v[154:155], s[4:5], 0, v[180:181]
	v_cvt_pk_f16_f32 v153, v44, v45
	v_cvt_pk_f16_f32 v152, v42, v43
	v_cvt_pk_f16_f32 v151, v48, v49
	v_cvt_pk_f16_f32 v150, v46, v47
	v_lshl_add_u64 v[154:155], v[154:155], 0, v[158:159]
	global_store_dwordx4 v[154:155], v[150:153], off
	s_waitcnt vmcnt(15)
	v_cvt_f32_f16_e32 v156, v211
	v_cvt_f32_f16_sdwa v157, v211 dst_sel:DWORD dst_unused:UNUSED_PAD src0_sel:WORD_1
	v_cvt_f32_f16_e32 v150, v213
	v_cvt_f32_f16_sdwa v151, v213 dst_sel:DWORD dst_unused:UNUSED_PAD src0_sel:WORD_1
	v_cvt_f32_f16_e32 v152, v212
	v_cvt_f32_f16_sdwa v153, v212 dst_sel:DWORD dst_unused:UNUSED_PAD src0_sel:WORD_1
	v_cvt_f32_f16_e32 v162, v210
	v_cvt_f32_f16_sdwa v163, v210 dst_sel:DWORD dst_unused:UNUSED_PAD src0_sel:WORD_1
	v_pk_add_f32 v[40:41], v[40:41], v[156:157]
	v_pk_add_f32 v[34:35], v[34:35], v[152:153]
	v_pk_add_f32 v[36:37], v[36:37], v[150:151]
	v_pk_add_f32 v[38:39], v[38:39], v[162:163]
	v_cvt_pk_f16_f32 v153, v36, v37
	v_cvt_pk_f16_f32 v152, v34, v35
	v_cvt_pk_f16_f32 v151, v40, v41
	v_cvt_pk_f16_f32 v150, v38, v39
	global_store_dwordx4 v[154:155], v[150:153], off offset:256
	s_waitcnt vmcnt(15)
	v_cvt_f32_f16_e32 v154, v214
	v_cvt_f32_f16_sdwa v155, v214 dst_sel:DWORD dst_unused:UNUSED_PAD src0_sel:WORD_1
	v_cvt_f32_f16_e32 v150, v217
	v_cvt_f32_f16_sdwa v151, v217 dst_sel:DWORD dst_unused:UNUSED_PAD src0_sel:WORD_1
	v_cvt_f32_f16_e32 v152, v216
	v_cvt_f32_f16_sdwa v153, v216 dst_sel:DWORD dst_unused:UNUSED_PAD src0_sel:WORD_1
	v_cvt_f32_f16_e32 v144, v215
	v_cvt_f32_f16_sdwa v145, v215 dst_sel:DWORD dst_unused:UNUSED_PAD src0_sel:WORD_1
	v_pk_add_f32 v[28:29], v[28:29], v[154:155]
	v_pk_add_f32 v[24:25], v[24:25], v[152:153]
	v_pk_add_f32 v[26:27], v[26:27], v[150:151]
	v_pk_add_f32 v[30:31], v[30:31], v[144:145]
	v_cvt_pk_f16_f32 v145, v26, v27
	v_cvt_pk_f16_f32 v144, v24, v25
	v_cvt_pk_f16_f32 v143, v30, v31
	v_cvt_pk_f16_f32 v142, v28, v29
	global_store_dwordx4 v[148:149], v[142:145], off
	s_waitcnt vmcnt(15)
; __device__ __forceinline__ float bf_lo(unsigned w) { return __uint_as_float(w << 16); }
; __device__ __forceinline__ float bf_hi(unsigned w) { return __uint_as_float(w & 0xffff0000u); }
; __device__ __forceinline__ float sigmoidf_fast(float x) { return __builtin_amdgcn_rcpf(1.0f + __expf(-x)); }
;     __device__ __forceinline__ void run(const f32x4 (&v)[2][2][4][2], const Unit& u, int wr, int wc, int fr, int fq, PG8_LAS unsigned char* lds, int wid, int lane, float inv_n, float eps) const {
;     ...
;         for (int ai = 0; ai < 2; ++ai)
; #pragma unroll
;             for (int m = 0; m < 4; ++m) {
;                 float s = 0.f;
; #pragma unroll
;                 for (int bj = 0; bj < 2; ++bj)
; #pragma unroll
;                     for (int n = 0; n < 2; ++n) { const f32x4 x = v[ai][bj][m][n]; s += (x[0] * x[0] + x[1] * x[1]) + (x[2] * x[2] + x[3] * x[3]); }
;                 s += __shfl_xor(s, 16); s += __shfl_xor(s, 32);
;                 if (fq == 0) P[(ai * HALF + wr * 64 + m * 16 + fr) * 4 + wc] = s;
;     __device__ __forceinline__ void fused(f32x4 (&acc)[2][2][4][2], const Unit& u, int wr, int wc, int fr, int fq, PG8_LAS unsigned char* lds, int wid, int lane) const {
;     ...
;             for (int m = 0; m < 4; ++m) { const size_t off = (size_t)(u.pm * BM + ai * HALF + wr * 64 + m * 16 + fr) * ld + col0;
; #pragma unroll
;                 for (int bj = 0; bj < 2; ++bj) { const f32x8 hv = __builtin_convertvector(hraw[m][bj], f32x8); f32x8 r8;
; #pragma unroll
;                     for (int n = 0; n < 2; ++n) { f32x4 r; const f32x4 a = acc[ai][bj][m][n];
;                         if (MODE == 0) { r[0] = hv[4 * n] + a[0]; r[1] = hv[4 * n + 1] + a[1]; r[2] = hv[4 * n + 2] + a[2]; r[3] = hv[4 * n + 3] + a[3]; }
;                         else { const unsigned e0 = n ? eraw[m][bj].z : eraw[m][bj].x, e1 = n ? eraw[m][bj].w : eraw[m][bj].y;
;                             r[0] = hv[4 * n] + sigmoidf_fast(a[0]) * bf_lo(e0); r[1] = hv[4 * n + 1] + sigmoidf_fast(a[1]) * bf_hi(e0); r[2] = hv[4 * n + 2] + sigmoidf_fast(a[2]) * bf_lo(e1); r[3] = hv[4 * n + 3] + sigmoidf_fast(a[3]) * bf_hi(e1); }
;                         acc[ai][bj][m][n] = r; r8[4 * n] = r[0]; r8[4 * n + 1] = r[1]; r8[4 * n + 2] = r[2]; r8[4 * n + 3] = r[3]; }
;                     *(h16x8*)(H + off + bj * HALF) = __builtin_convertvector(r8, h16x8); }
	v_cvt_f32_f16_e32 v150, v218
	v_cvt_f32_f16_sdwa v151, v218 dst_sel:DWORD dst_unused:UNUSED_PAD src0_sel:WORD_1
	v_cvt_f32_f16_e32 v142, v221
	v_cvt_f32_f16_sdwa v143, v221 dst_sel:DWORD dst_unused:UNUSED_PAD src0_sel:WORD_1
	v_cvt_f32_f16_e32 v144, v220
	v_cvt_f32_f16_sdwa v145, v220 dst_sel:DWORD dst_unused:UNUSED_PAD src0_sel:WORD_1
	v_cvt_f32_f16_e32 v140, v219
	v_cvt_f32_f16_sdwa v141, v219 dst_sel:DWORD dst_unused:UNUSED_PAD src0_sel:WORD_1
	v_pk_add_f32 v[20:21], v[20:21], v[150:151]
	v_pk_add_f32 v[16:17], v[16:17], v[144:145]
	v_pk_add_f32 v[18:19], v[18:19], v[142:143]
	v_pk_add_f32 v[22:23], v[22:23], v[140:141]
	v_cvt_pk_f16_f32 v141, v18, v19
	v_cvt_pk_f16_f32 v140, v16, v17
	v_cvt_pk_f16_f32 v139, v22, v23
	v_cvt_pk_f16_f32 v138, v20, v21
	global_store_dwordx4 v[148:149], v[138:141], off offset:256
	s_waitcnt vmcnt(15)
	v_cvt_f32_f16_e32 v142, v222
	v_cvt_f32_f16_sdwa v143, v222 dst_sel:DWORD dst_unused:UNUSED_PAD src0_sel:WORD_1
	v_cvt_f32_f16_e32 v138, v225
	v_cvt_f32_f16_sdwa v139, v225 dst_sel:DWORD dst_unused:UNUSED_PAD src0_sel:WORD_1
	v_cvt_f32_f16_e32 v140, v224
	v_cvt_f32_f16_sdwa v141, v224 dst_sel:DWORD dst_unused:UNUSED_PAD src0_sel:WORD_1
	v_cvt_f32_f16_e32 v136, v223
	v_cvt_f32_f16_sdwa v137, v223 dst_sel:DWORD dst_unused:UNUSED_PAD src0_sel:WORD_1
	v_pk_add_f32 v[12:13], v[12:13], v[142:143]
	v_pk_add_f32 v[8:9], v[8:9], v[140:141]
	v_pk_add_f32 v[10:11], v[10:11], v[138:139]
	v_pk_add_f32 v[14:15], v[14:15], v[136:137]
	v_lshl_add_u64 v[138:139], s[4:5], 0, v[146:147]
	v_cvt_pk_f16_f32 v137, v10, v11
	v_cvt_pk_f16_f32 v136, v8, v9
	v_cvt_pk_f16_f32 v135, v14, v15
	v_cvt_pk_f16_f32 v134, v12, v13
	v_lshl_add_u64 v[138:139], v[138:139], 0, v[158:159]
	global_store_dwordx4 v[138:139], v[134:137], off
	s_waitcnt vmcnt(15)
	v_cvt_f32_f16_e32 v140, v246
	v_cvt_f32_f16_sdwa v141, v246 dst_sel:DWORD dst_unused:UNUSED_PAD src0_sel:WORD_1
	v_cvt_f32_f16_e32 v134, v249
	v_cvt_f32_f16_sdwa v135, v249 dst_sel:DWORD dst_unused:UNUSED_PAD src0_sel:WORD_1
	v_cvt_f32_f16_e32 v136, v248
	v_cvt_f32_f16_sdwa v137, v248 dst_sel:DWORD dst_unused:UNUSED_PAD src0_sel:WORD_1
	v_cvt_f32_f16_e32 v132, v247
	v_cvt_f32_f16_sdwa v133, v247 dst_sel:DWORD dst_unused:UNUSED_PAD src0_sel:WORD_1
	v_pk_add_f32 v[4:5], v[4:5], v[140:141]
	v_pk_add_f32 v[0:1], v[0:1], v[136:137]
	v_pk_add_f32 v[2:3], v[2:3], v[134:135]
	v_pk_add_f32 v[6:7], v[6:7], v[132:133]
	v_cvt_pk_f16_f32 v133, v2, v3
	v_cvt_pk_f16_f32 v132, v0, v1
	v_cvt_pk_f16_f32 v131, v6, v7
	v_cvt_pk_f16_f32 v130, v4, v5
	global_store_dwordx4 v[138:139], v[130:133], off offset:256
	v_mul_f32_e32 v134, v117, v117
	v_fmac_f32_e32 v134, v116, v116
	v_and_b32_e32 v131, 64, v236
	v_xor_b32_e32 v130, 16, v236
	v_add_u32_e32 v131, 64, v131
	v_cmp_lt_i32_e32 vcc, v130, v131
	v_xor_b32_e32 v132, 32, v236
	v_mul_f32_e32 v133, v121, v121
	v_cndmask_b32_e32 v130, v236, v130, vcc
	v_cmp_lt_i32_e32 vcc, v132, v131
	v_fmac_f32_e32 v133, v120, v120
	v_lshlrev_b32_e32 v130, 2, v130
	v_cndmask_b32_e32 v131, v236, v132, vcc
	v_mul_f32_e32 v132, v119, v119
	v_fmac_f32_e32 v132, v118, v118
	v_add_f32_e32 v132, v132, v133
	v_mul_f32_e32 v133, v115, v115
	v_fmac_f32_e32 v133, v114, v114
	v_add_f32_e32 v133, v133, v134
	v_add_f32_e32 v132, v132, v133
	v_mul_f32_e32 v133, v127, v127
	v_mul_f32_e32 v134, v129, v129
	v_fmac_f32_e32 v133, v126, v126
	v_fmac_f32_e32 v134, v128, v128
	v_add_f32_e32 v133, v133, v134
	v_add_f32_e32 v132, v133, v132
	v_mul_f32_e32 v133, v123, v123
	v_mul_f32_e32 v134, v125, v125
	v_fmac_f32_e32 v133, v122, v122
	v_fmac_f32_e32 v134, v124, v124
	v_add_f32_e32 v133, v133, v134
	v_add_f32_e32 v132, v133, v132
	ds_bpermute_b32 v133, v130, v132
	v_lshlrev_b32_e32 v131, 2, v131
	s_lshl_b32 s4, s36, 2
	s_waitcnt lgkmcnt(0)
	v_add_f32_e32 v132, v132, v133
	ds_bpermute_b32 v133, v131, v132
	v_cmp_gt_u32_e32 vcc, 16, v32
	s_add_i32 s10, s4, 0
	s_and_saveexec_b64 s[4:5], vcc
	s_cbranch_execz .LBB0_1179
	s_lshl_b32 s11, s20, 10
	s_add_i32 s11, s10, s11
	v_lshl_add_u32 v134, v174, 4, s11
	s_waitcnt lgkmcnt(0)
	v_add_f32_e32 v132, v132, v133
	ds_write_b32 v134, v132
